# GU epilogue: single base store address + SGPR soffset per site (no per-site VALU address chains), row scales read straight from prefetch regs, dead row adds removed
# speedup vs baseline: 1.0107x; 1.0025x over previous
.LBB0_788:
	s_waitcnt lgkmcnt(0)
	v_mul_f32_e32 v246, 0xbfb8aa3b, v221
	v_mul_f32_e32 v247, v221, v221
	v_rcp_f32_e32 v247, v247
	v_mul_f32_e32 v8, v8, v12
	v_mul_f32_e32 v9, v9, v13
	v_mul_f32_e32 v10, v10, v14
	v_mul_f32_e32 v11, v11, v15
	v_mul_f32_e32 v0, v0, v4
	v_mul_f32_e32 v1, v1, v5
	v_mul_f32_e32 v2, v2, v6
	v_mul_f32_e32 v3, v3, v7
	v_mul_f32_e32 v12, v246, v12
	v_mul_f32_e32 v13, v246, v13
	v_mul_f32_e32 v14, v246, v14
	v_mul_f32_e32 v15, v246, v15
	v_mul_f32_e32 v4, v246, v4
	v_mul_f32_e32 v5, v246, v5
	v_mul_f32_e32 v6, v246, v6
	v_mul_f32_e32 v7, v246, v7
	v_exp_f32_e32 v12, v12
	v_exp_f32_e32 v13, v13
	v_exp_f32_e32 v14, v14
	v_exp_f32_e32 v15, v15
	v_exp_f32_e32 v4, v4
	v_exp_f32_e32 v5, v5
	v_exp_f32_e32 v6, v6
	v_exp_f32_e32 v7, v7
	v_fma_f32 v12, v12, v247, v247
	v_fma_f32 v13, v13, v247, v247
	v_fma_f32 v14, v14, v247, v247
	v_fma_f32 v15, v15, v247, v247
	v_fma_f32 v4, v4, v247, v247
	v_fma_f32 v5, v5, v247, v247
	v_fma_f32 v6, v6, v247, v247
	v_fma_f32 v7, v7, v247, v247
	v_rcp_f32_e32 v12, v12
	v_rcp_f32_e32 v13, v13
	v_rcp_f32_e32 v14, v14
	v_rcp_f32_e32 v15, v15
	v_rcp_f32_e32 v4, v4
	v_rcp_f32_e32 v5, v5
	v_rcp_f32_e32 v6, v6
	v_rcp_f32_e32 v7, v7
	v_mul_f32_e32 v8, v8, v12
	v_mul_f32_e32 v9, v9, v13
	v_mul_f32_e32 v10, v10, v14
	v_mul_f32_e32 v11, v11, v15
	v_mul_f32_e32 v0, v0, v4
	v_mul_f32_e32 v1, v1, v5
	v_mul_f32_e32 v2, v2, v6
	v_mul_f32_e32 v3, v3, v7
	v_cvt_pk_bf16_f32 v12, v8, v9
	v_cvt_pk_bf16_f32 v13, v10, v11
	v_cvt_pk_bf16_f32 v14, v0, v1
	v_cvt_pk_bf16_f32 v15, v2, v3
	s_and_b64 vcc, exec, s[6:7]
	s_mov_b32 s8, s18
	s_mov_b32 s28, s20
	s_mov_b64 s[62:63], s[24:25]
	s_mov_b64 s[58:59], s[22:23]
	s_mov_b32 s1, 0xf2000
	buffer_store_dwordx4 v[12:15], v222, s[36:39], s1 offen sc1
	s_cbranch_vccnz .LBB0_825

.Lzp_exit3:
	s_lshl_b32 s19, s28, 8
	v_add_u32_e32 v138, s19, v141
	ds_read_b32 v140, v143
	ds_read_b32 v215, v143 offset:64
	ds_read_b32 v216, v143 offset:128
	ds_read_b32 v217, v143 offset:192
	ds_read_b32 v218, v143 offset:512
	ds_read_b32 v219, v143 offset:576
	ds_read_b32 v220, v143 offset:640
	ds_read_b32 v221, v143 offset:704
	s_waitcnt lgkmcnt(0)
	v_mul_f32_e32 v246, 0xbfb8aa3b, v140
	v_mul_f32_e32 v247, v140, v140
	v_rcp_f32_e32 v247, v247
	v_mul_f32_e32 v120, v120, v124
	v_mul_f32_e32 v121, v121, v125
	v_mul_f32_e32 v122, v122, v126
	v_mul_f32_e32 v123, v123, v127
	v_mul_f32_e32 v112, v112, v116
	v_mul_f32_e32 v113, v113, v117
	v_mul_f32_e32 v114, v114, v118
	v_mul_f32_e32 v115, v115, v119
	v_mul_f32_e32 v124, v246, v124
	v_mul_f32_e32 v125, v246, v125
	v_mul_f32_e32 v126, v246, v126
	v_mul_f32_e32 v127, v246, v127
	v_mul_f32_e32 v116, v246, v116
	v_mul_f32_e32 v117, v246, v117
	v_mul_f32_e32 v118, v246, v118
	v_mul_f32_e32 v119, v246, v119
	v_exp_f32_e32 v124, v124
	v_exp_f32_e32 v125, v125
	v_exp_f32_e32 v126, v126
	v_exp_f32_e32 v127, v127
	v_exp_f32_e32 v116, v116
	v_exp_f32_e32 v117, v117
	v_exp_f32_e32 v118, v118
	v_exp_f32_e32 v119, v119
	v_fma_f32 v124, v124, v247, v247
	v_fma_f32 v125, v125, v247, v247
	v_fma_f32 v126, v126, v247, v247
	v_fma_f32 v127, v127, v247, v247
	v_fma_f32 v116, v116, v247, v247
	v_fma_f32 v117, v117, v247, v247
	v_fma_f32 v118, v118, v247, v247
	v_fma_f32 v119, v119, v247, v247
	v_rcp_f32_e32 v124, v124
	v_rcp_f32_e32 v125, v125
	v_rcp_f32_e32 v126, v126
	v_rcp_f32_e32 v127, v127
	v_rcp_f32_e32 v116, v116
	v_rcp_f32_e32 v117, v117
	v_rcp_f32_e32 v118, v118
	v_rcp_f32_e32 v119, v119
	v_mul_f32_e32 v120, v120, v124
	v_mul_f32_e32 v121, v121, v125
	v_mul_f32_e32 v122, v122, v126
	v_mul_f32_e32 v123, v123, v127
	v_mul_f32_e32 v112, v112, v116
	v_mul_f32_e32 v113, v113, v117
	v_mul_f32_e32 v114, v114, v118
	v_mul_f32_e32 v115, v115, v119
	v_cvt_pk_bf16_f32 v124, v120, v121
	v_cvt_pk_bf16_f32 v125, v122, v123
	v_cvt_pk_bf16_f32 v126, v112, v113
	v_cvt_pk_bf16_f32 v127, v114, v115
	s_movk_i32 s1, 0xb00
	v_lshl_or_b32 v139, s8, 7, v144
	v_mul_lo_u32 v113, v138, s1
	v_add_lshl_u32 v222, v113, v139, 1
	buffer_store_dwordx4 v[124:127], v222, s[36:39], 0 offen sc1
	v_mul_f32_e32 v246, 0xbfb8aa3b, v215
	v_mul_f32_e32 v247, v215, v215
	v_rcp_f32_e32 v247, v247
	v_mul_f32_e32 v104, v104, v108
	v_mul_f32_e32 v105, v105, v109
	v_mul_f32_e32 v106, v106, v110
	v_mul_f32_e32 v107, v107, v111
	v_mul_f32_e32 v96, v96, v100
	v_mul_f32_e32 v97, v97, v101
	v_mul_f32_e32 v98, v98, v102
	v_mul_f32_e32 v99, v99, v103
	v_mul_f32_e32 v108, v246, v108
	v_mul_f32_e32 v109, v246, v109
	v_mul_f32_e32 v110, v246, v110
	v_mul_f32_e32 v111, v246, v111
	v_mul_f32_e32 v100, v246, v100
	v_mul_f32_e32 v101, v246, v101
	v_mul_f32_e32 v102, v246, v102
	v_mul_f32_e32 v103, v246, v103
	v_exp_f32_e32 v108, v108
	v_exp_f32_e32 v109, v109
	v_exp_f32_e32 v110, v110
	v_exp_f32_e32 v111, v111
	v_exp_f32_e32 v100, v100
	v_exp_f32_e32 v101, v101
	v_exp_f32_e32 v102, v102
	v_exp_f32_e32 v103, v103
	v_fma_f32 v108, v108, v247, v247
	v_fma_f32 v109, v109, v247, v247
	v_fma_f32 v110, v110, v247, v247
	v_fma_f32 v111, v111, v247, v247
	v_fma_f32 v100, v100, v247, v247
	v_fma_f32 v101, v101, v247, v247
	v_fma_f32 v102, v102, v247, v247
	v_fma_f32 v103, v103, v247, v247
	v_rcp_f32_e32 v108, v108
	v_rcp_f32_e32 v109, v109
	v_rcp_f32_e32 v110, v110
	v_rcp_f32_e32 v111, v111
	v_rcp_f32_e32 v100, v100
	v_rcp_f32_e32 v101, v101
	v_rcp_f32_e32 v102, v102
	v_rcp_f32_e32 v103, v103
	v_mul_f32_e32 v104, v104, v108
	v_mul_f32_e32 v105, v105, v109
	v_mul_f32_e32 v106, v106, v110
	v_mul_f32_e32 v107, v107, v111
	v_mul_f32_e32 v96, v96, v100
	v_mul_f32_e32 v97, v97, v101
	v_mul_f32_e32 v98, v98, v102
	v_mul_f32_e32 v99, v99, v103
	v_cvt_pk_bf16_f32 v108, v104, v105
	v_cvt_pk_bf16_f32 v109, v106, v107
	v_cvt_pk_bf16_f32 v110, v96, v97
	v_cvt_pk_bf16_f32 v111, v98, v99
	s_mov_b32 s1, 0x16000
	buffer_store_dwordx4 v[108:111], v222, s[36:39], s1 offen sc1
	s_nop 1
	v_mul_f32_e32 v246, 0xbfb8aa3b, v216
	v_mul_f32_e32 v247, v216, v216
	v_rcp_f32_e32 v247, v247
	v_mul_f32_e32 v88, v88, v92
	v_mul_f32_e32 v89, v89, v93
	v_mul_f32_e32 v90, v90, v94
	v_mul_f32_e32 v91, v91, v95
	v_mul_f32_e32 v80, v80, v84
	v_mul_f32_e32 v81, v81, v85
	v_mul_f32_e32 v82, v82, v86
	v_mul_f32_e32 v83, v83, v87
	v_mul_f32_e32 v92, v246, v92
	v_mul_f32_e32 v93, v246, v93
	v_mul_f32_e32 v94, v246, v94
	v_mul_f32_e32 v95, v246, v95
	v_mul_f32_e32 v84, v246, v84
	v_mul_f32_e32 v85, v246, v85
	v_mul_f32_e32 v86, v246, v86
	v_mul_f32_e32 v87, v246, v87
	v_exp_f32_e32 v92, v92
	v_exp_f32_e32 v93, v93
	v_exp_f32_e32 v94, v94
	v_exp_f32_e32 v95, v95
	v_exp_f32_e32 v84, v84
	v_exp_f32_e32 v85, v85
	v_exp_f32_e32 v86, v86
	v_exp_f32_e32 v87, v87
	v_fma_f32 v92, v92, v247, v247
	v_fma_f32 v93, v93, v247, v247
	v_fma_f32 v94, v94, v247, v247
	v_fma_f32 v95, v95, v247, v247
	v_fma_f32 v84, v84, v247, v247
	v_fma_f32 v85, v85, v247, v247
	v_fma_f32 v86, v86, v247, v247
	v_fma_f32 v87, v87, v247, v247
	v_rcp_f32_e32 v92, v92
	v_rcp_f32_e32 v93, v93
	v_rcp_f32_e32 v94, v94
	v_rcp_f32_e32 v95, v95
	v_rcp_f32_e32 v84, v84
	v_rcp_f32_e32 v85, v85
	v_rcp_f32_e32 v86, v86
	v_rcp_f32_e32 v87, v87
	v_mul_f32_e32 v88, v88, v92
	v_mul_f32_e32 v89, v89, v93
	v_mul_f32_e32 v90, v90, v94
	v_mul_f32_e32 v91, v91, v95
	v_mul_f32_e32 v80, v80, v84
	v_mul_f32_e32 v81, v81, v85
	v_mul_f32_e32 v82, v82, v86
	v_mul_f32_e32 v83, v83, v87
	v_cvt_pk_bf16_f32 v92, v88, v89
	v_cvt_pk_bf16_f32 v93, v90, v91
	v_cvt_pk_bf16_f32 v94, v80, v81
	v_cvt_pk_bf16_f32 v95, v82, v83
	s_mov_b32 s1, 0x2c000
	buffer_store_dwordx4 v[92:95], v222, s[36:39], s1 offen sc1
	s_nop 1
	v_mul_f32_e32 v246, 0xbfb8aa3b, v217
	v_mul_f32_e32 v247, v217, v217
	v_rcp_f32_e32 v247, v247
	v_mul_f32_e32 v72, v72, v76
	v_mul_f32_e32 v73, v73, v77
	v_mul_f32_e32 v74, v74, v78
	v_mul_f32_e32 v75, v75, v79
	v_mul_f32_e32 v64, v64, v68
	v_mul_f32_e32 v65, v65, v69
	v_mul_f32_e32 v66, v66, v70
	v_mul_f32_e32 v67, v67, v71
	v_mul_f32_e32 v76, v246, v76
	v_mul_f32_e32 v77, v246, v77
	v_mul_f32_e32 v78, v246, v78
	v_mul_f32_e32 v79, v246, v79
	v_mul_f32_e32 v68, v246, v68
	v_mul_f32_e32 v69, v246, v69
	v_mul_f32_e32 v70, v246, v70
	v_mul_f32_e32 v71, v246, v71
	v_exp_f32_e32 v76, v76
	v_exp_f32_e32 v77, v77
	v_exp_f32_e32 v78, v78
	v_exp_f32_e32 v79, v79
	v_exp_f32_e32 v68, v68
	v_exp_f32_e32 v69, v69
	v_exp_f32_e32 v70, v70
	v_exp_f32_e32 v71, v71
	v_fma_f32 v76, v76, v247, v247
	v_fma_f32 v77, v77, v247, v247
	v_fma_f32 v78, v78, v247, v247
	v_fma_f32 v79, v79, v247, v247
	v_fma_f32 v68, v68, v247, v247
	v_fma_f32 v69, v69, v247, v247
	v_fma_f32 v70, v70, v247, v247
	v_fma_f32 v71, v71, v247, v247
	v_rcp_f32_e32 v76, v76
	v_rcp_f32_e32 v77, v77
	v_rcp_f32_e32 v78, v78
	v_rcp_f32_e32 v79, v79
	v_rcp_f32_e32 v68, v68
	v_rcp_f32_e32 v69, v69
	v_rcp_f32_e32 v70, v70
	v_rcp_f32_e32 v71, v71
	v_mul_f32_e32 v72, v72, v76
	v_mul_f32_e32 v73, v73, v77
	v_mul_f32_e32 v74, v74, v78
	v_mul_f32_e32 v75, v75, v79
	v_mul_f32_e32 v64, v64, v68
	v_mul_f32_e32 v65, v65, v69
	v_mul_f32_e32 v66, v66, v70
	v_mul_f32_e32 v67, v67, v71
	v_cvt_pk_bf16_f32 v76, v72, v73
	v_cvt_pk_bf16_f32 v77, v74, v75
	v_cvt_pk_bf16_f32 v78, v64, v65
	v_cvt_pk_bf16_f32 v79, v66, v67
	s_mov_b32 s1, 0x42000
	buffer_store_dwordx4 v[76:79], v222, s[36:39], s1 offen sc1
	s_nop 1
	v_mul_f32_e32 v246, 0xbfb8aa3b, v218
	v_mul_f32_e32 v247, v218, v218
	v_rcp_f32_e32 v247, v247
	v_mul_f32_e32 v56, v56, v60
	v_mul_f32_e32 v57, v57, v61
	v_mul_f32_e32 v58, v58, v62
	v_mul_f32_e32 v59, v59, v63
	v_mul_f32_e32 v48, v48, v52
	v_mul_f32_e32 v49, v49, v53
	v_mul_f32_e32 v50, v50, v54
	v_mul_f32_e32 v51, v51, v55
	v_mul_f32_e32 v60, v246, v60
	v_mul_f32_e32 v61, v246, v61
	v_mul_f32_e32 v62, v246, v62
	v_mul_f32_e32 v63, v246, v63
	v_mul_f32_e32 v52, v246, v52
	v_mul_f32_e32 v53, v246, v53
	v_mul_f32_e32 v54, v246, v54
	v_mul_f32_e32 v55, v246, v55
	v_exp_f32_e32 v60, v60
	v_exp_f32_e32 v61, v61
	v_exp_f32_e32 v62, v62
	v_exp_f32_e32 v63, v63
	v_exp_f32_e32 v52, v52
	v_exp_f32_e32 v53, v53
	v_exp_f32_e32 v54, v54
	v_exp_f32_e32 v55, v55
	v_fma_f32 v60, v60, v247, v247
	v_fma_f32 v61, v61, v247, v247
	v_fma_f32 v62, v62, v247, v247
	v_fma_f32 v63, v63, v247, v247
	v_fma_f32 v52, v52, v247, v247
	v_fma_f32 v53, v53, v247, v247
	v_fma_f32 v54, v54, v247, v247
	v_fma_f32 v55, v55, v247, v247
	v_rcp_f32_e32 v60, v60
	v_rcp_f32_e32 v61, v61
	v_rcp_f32_e32 v62, v62
	v_rcp_f32_e32 v63, v63
	v_rcp_f32_e32 v52, v52
	v_rcp_f32_e32 v53, v53
	v_rcp_f32_e32 v54, v54
	v_rcp_f32_e32 v55, v55
	v_mul_f32_e32 v56, v56, v60
	v_mul_f32_e32 v57, v57, v61
	v_mul_f32_e32 v58, v58, v62
	v_mul_f32_e32 v59, v59, v63
	v_mul_f32_e32 v48, v48, v52
	v_mul_f32_e32 v49, v49, v53
	v_mul_f32_e32 v50, v50, v54
	v_mul_f32_e32 v51, v51, v55
	v_cvt_pk_bf16_f32 v60, v56, v57
	v_cvt_pk_bf16_f32 v61, v58, v59
	v_cvt_pk_bf16_f32 v62, v48, v49
	v_cvt_pk_bf16_f32 v63, v50, v51
	s_mov_b32 s1, 0xb0000
	buffer_store_dwordx4 v[60:63], v222, s[36:39], s1 offen sc1
	s_nop 1
	v_mul_f32_e32 v246, 0xbfb8aa3b, v219
	v_mul_f32_e32 v247, v219, v219
	v_rcp_f32_e32 v247, v247
	v_mul_f32_e32 v40, v40, v44
	v_mul_f32_e32 v41, v41, v45
	v_mul_f32_e32 v42, v42, v46
	v_mul_f32_e32 v43, v43, v47
	v_mul_f32_e32 v32, v32, v36
	v_mul_f32_e32 v33, v33, v37
	v_mul_f32_e32 v34, v34, v38
	v_mul_f32_e32 v35, v35, v39
	v_mul_f32_e32 v44, v246, v44
	v_mul_f32_e32 v45, v246, v45
	v_mul_f32_e32 v46, v246, v46
	v_mul_f32_e32 v47, v246, v47
	v_mul_f32_e32 v36, v246, v36
	v_mul_f32_e32 v37, v246, v37
	v_mul_f32_e32 v38, v246, v38
	v_mul_f32_e32 v39, v246, v39
	v_exp_f32_e32 v44, v44
	v_exp_f32_e32 v45, v45
	v_exp_f32_e32 v46, v46
	v_exp_f32_e32 v47, v47
	v_exp_f32_e32 v36, v36
	v_exp_f32_e32 v37, v37
	v_exp_f32_e32 v38, v38
	v_exp_f32_e32 v39, v39
	v_fma_f32 v44, v44, v247, v247
	v_fma_f32 v45, v45, v247, v247
	v_fma_f32 v46, v46, v247, v247
	v_fma_f32 v47, v47, v247, v247
	v_fma_f32 v36, v36, v247, v247
	v_fma_f32 v37, v37, v247, v247
	v_fma_f32 v38, v38, v247, v247
	v_fma_f32 v39, v39, v247, v247
	v_rcp_f32_e32 v44, v44
	v_rcp_f32_e32 v45, v45
	v_rcp_f32_e32 v46, v46
	v_rcp_f32_e32 v47, v47
	v_rcp_f32_e32 v36, v36
	v_rcp_f32_e32 v37, v37
	v_rcp_f32_e32 v38, v38
	v_rcp_f32_e32 v39, v39
	v_mul_f32_e32 v40, v40, v44
	v_mul_f32_e32 v41, v41, v45
	v_mul_f32_e32 v42, v42, v46
	v_mul_f32_e32 v43, v43, v47
	v_mul_f32_e32 v32, v32, v36
	v_mul_f32_e32 v33, v33, v37
	v_mul_f32_e32 v34, v34, v38
	v_mul_f32_e32 v35, v35, v39
	v_cvt_pk_bf16_f32 v44, v40, v41
	v_cvt_pk_bf16_f32 v45, v42, v43
	v_cvt_pk_bf16_f32 v46, v32, v33
	v_cvt_pk_bf16_f32 v47, v34, v35
	s_mov_b32 s1, 0xc6000
	buffer_store_dwordx4 v[44:47], v222, s[36:39], s1 offen sc1
	v_mul_f32_e32 v246, 0xbfb8aa3b, v220
	v_mul_f32_e32 v247, v220, v220
	v_rcp_f32_e32 v247, v247
	v_mul_f32_e32 v24, v24, v28
	v_mul_f32_e32 v25, v25, v29
	v_mul_f32_e32 v26, v26, v30
	v_mul_f32_e32 v27, v27, v31
	v_mul_f32_e32 v16, v16, v20
	v_mul_f32_e32 v17, v17, v21
	v_mul_f32_e32 v18, v18, v22
	v_mul_f32_e32 v19, v19, v23
	v_mul_f32_e32 v28, v246, v28
	v_mul_f32_e32 v29, v246, v29
	v_mul_f32_e32 v30, v246, v30
	v_mul_f32_e32 v31, v246, v31
	v_mul_f32_e32 v20, v246, v20
	v_mul_f32_e32 v21, v246, v21
	v_mul_f32_e32 v22, v246, v22
	v_mul_f32_e32 v23, v246, v23
	v_exp_f32_e32 v28, v28
	v_exp_f32_e32 v29, v29
	v_exp_f32_e32 v30, v30
	v_exp_f32_e32 v31, v31
	v_exp_f32_e32 v20, v20
	v_exp_f32_e32 v21, v21
	v_exp_f32_e32 v22, v22
	v_exp_f32_e32 v23, v23
	v_fma_f32 v28, v28, v247, v247
	v_fma_f32 v29, v29, v247, v247
	v_fma_f32 v30, v30, v247, v247
	v_fma_f32 v31, v31, v247, v247
	v_fma_f32 v20, v20, v247, v247
	v_fma_f32 v21, v21, v247, v247
	v_fma_f32 v22, v22, v247, v247
	v_fma_f32 v23, v23, v247, v247
	v_rcp_f32_e32 v28, v28
	v_rcp_f32_e32 v29, v29
	v_rcp_f32_e32 v30, v30
	v_rcp_f32_e32 v31, v31
	v_rcp_f32_e32 v20, v20
	v_rcp_f32_e32 v21, v21
	v_rcp_f32_e32 v22, v22
	v_rcp_f32_e32 v23, v23
	v_mul_f32_e32 v24, v24, v28
	v_mul_f32_e32 v25, v25, v29
	v_mul_f32_e32 v26, v26, v30
	v_mul_f32_e32 v27, v27, v31
	v_mul_f32_e32 v16, v16, v20
	v_mul_f32_e32 v17, v17, v21
	v_mul_f32_e32 v18, v18, v22
	v_mul_f32_e32 v19, v19, v23
	v_cvt_pk_bf16_f32 v28, v24, v25
	v_cvt_pk_bf16_f32 v29, v26, v27
	v_cvt_pk_bf16_f32 v30, v16, v17
	v_cvt_pk_bf16_f32 v31, v18, v19
	s_mov_b32 s1, 0xdc000
	buffer_store_dwordx4 v[28:31], v222, s[36:39], s1 offen sc1
	s_nop 1
	s_branch .LBB0_788
